# defer
# speedup vs baseline: 1.0010x; 1.0010x over previous
; __device__ void phase_proj(const Params& p, char* smem, const XcdBarrier& xb) {
;     ...
;   DYN_TILE_LOOP(xb, 0, 128, 24, mt, nt) {
.LBB0_160:
	s_mul_hi_i32 s4, s6, 0x2aaaaaab
	s_lshr_b32 s5, s4, 31
	s_ashr_i32 s10, s4, 2
	s_add_i32 s10, s10, s5
	s_mul_i32 s39, s10, s33
	s_add_i32 s39, s39, s18
	s_cmpk_gt_i32 s39, 0x7f
	s_mov_b64 s[4:5], -1
	s_cbranch_scc1 .LBB0_159
	v_mov_b32_e32 v110, 0
	s_and_saveexec_b64 s[4:5], s[0:1]
	s_cbranch_execz .LBB0_163
	global_atomic_add v110, v[96:97], v108, off sc0

; __device__ __forceinline__ int dyn_tile_next(int nxt) {
;   __syncthreads();
;   if (threadIdx.x == 0) s_next_tile = nxt;
;   __syncthreads();
;   return __builtin_amdgcn_readfirstlane(s_next_tile);
; }
.LBB0_171:
	global_store_dword v[0:1], v2, off offset:4
	s_barrier
	s_and_saveexec_b64 s[4:5], s[0:1]
	s_cbranch_execz .LBB0_158
	v_add_u32_e32 v110, s90, v110
	ds_write_b32 v109, v110
	s_branch .LBB0_158

; __device__ __forceinline__ unsigned xb_add(unsigned* p, unsigned v) { return __hip_atomic_fetch_add(p, v, __ATOMIC_RELAXED, __HIP_MEMORY_SCOPE_AGENT); }
; __device__ void phase_chain(const Params& p, char* smem, const XcdBarrier& xb) {
;     ...
;   while (L < total) {
;     const int nxt = (threadIdx.x == 0) ? (int)xb_add(&bar[XB_DYN(5, xb.x)], 1u) + nloc : 0;
;     int ph, mi, sub;
;     if (L < 4 * n8) { ph = L / n8; const int r = L - ph * n8; mi = r >> 3; sub = r & 7; }
;     else { ph = 4; const int r = L - 4 * n8; mi = r >> 4; sub = r & 15; }
;     const int mt = xi + nx * mi;
.LBB0_314:
	v_mov_b32_e32 v139, 0
	s_and_saveexec_b64 s[4:5], s[0:1]
	s_cbranch_execz .LBB0_316
	global_atomic_add v139, v[102:103], v120, off sc0

; __device__ __forceinline__ unsigned xb_add(unsigned* p, unsigned v) { return __hip_atomic_fetch_add(p, v, __ATOMIC_RELAXED, __HIP_MEMORY_SCOPE_AGENT); }
; __device__ __forceinline__ int dyn_tile_next(int nxt) {
;   __syncthreads();
;   if (threadIdx.x == 0) s_next_tile = nxt;
;   __syncthreads();
;   return __builtin_amdgcn_readfirstlane(s_next_tile);
; }
; __device__ void phase_chain(const Params& p, char* smem, const XcdBarrier& xb) {
;     ...
;     asm volatile("s_waitcnt vmcnt(0)" ::: "memory");
;     __syncthreads();
;     if (threadIdx.x == 0 && ph < 4) xb_add(&bar[XB_DONE(ph, mt)], 1u);
;     L = dyn_tile_next(nxt);
.LBB0_461:
	s_or_b64 exec, exec, s[4:5]
	s_barrier
	s_and_saveexec_b64 s[4:5], s[0:1]
	s_cbranch_execz .LBB0_313
	v_add_u32_e32 v139, s90, v139
	ds_write_b32 v123, v139
	s_branch .LBB0_313
